# v75: bias handled in the hand-written residual epilogue so the Fourier mixer's norm is folded too; last 32 column blocks of layer-0 adaLN moved from the prologue to idle workgroups of step 8
# speedup vs baseline: 1.0043x; 1.0043x over previous
.LBB0_8:
	v_readlane_b32 s6, v254, 61
	s_add_i32 s6, s6, 1
	s_cmp_eq_u32 s6, 35
	v_readlane_b32 s7, v254, 62
	s_cbranch_scc0 .LBB0_9
	s_getpc_b64 s[98:99]

.LBB0_551:
	s_and_b64 vcc, exec, s[2:3]
	s_cbranch_vccz .LBB0_561
	s_lshl_b32 s2, s17, 8
	s_addk_i32 s2, 0xe000
	s_ashr_i32 s2, s2, 11
	s_mulk_i32 s2, 0x2400
	s_addk_i32 s2, 0x2400
	s_cmp_lt_i32 s17, 32
	s_cselect_b32 s2, 0, s2
	s_lshl_b32 s2, s2, 2
	s_add_u32 s8, s36, s2
	s_addc_u32 s9, s37, 0
	v_readlane_b32 s12, v255, 5
	v_readlane_b32 s13, v255, 6
	s_mov_b64 s[10:11], s[12:13]
	v_readlane_b32 s2, v255, 61
	v_readlane_b32 s3, v255, 62
	s_and_b64 vcc, exec, s[2:3]
	s_cbranch_vccnz .Lres_src
	v_readlane_b32 s10, v255, 53
	v_readlane_b32 s11, v255, 54
	s_cmp_lt_i32 s17, 32
	s_cbranch_scc1 .Lres_src
	v_readlane_b32 s10, v255, 57
	v_readlane_b32 s11, v255, 58
.Lres_src:
	s_lshl_b32 s2, s48, 8
	s_or_b32 s2, s2, s68
	v_lshl_add_u32 v250, v239, 2, s2
	v_lshlrev_b32_e32 v250, 2, v250
	v_lshlrev_b32_e32 v249, 12, v186
	v_add_u32_e32 v248, v249, v250
	v_readlane_b32 s14, v255, 30
	v_readlane_b32 s15, v255, 31
	s_and_b64 vcc, exec, s[14:15]
	s_cbranch_vccz .Lres_nobias
	v_readlane_b32 s14, v255, 20
	v_readlane_b32 s15, v255, 21
	s_nop 4
	global_load_dwordx4 v[130:133], v250, s[14:15] offset:0
	global_load_dwordx4 v[134:137], v250, s[14:15] offset:64
	global_load_dwordx4 v[138:141], v250, s[14:15] offset:512
	global_load_dwordx4 v[142:145], v250, s[14:15] offset:576
	s_waitcnt vmcnt(0)
	v_pk_add_f32 v[126:127], v[126:127], v[130:131]
	v_pk_add_f32 v[128:129], v[128:129], v[132:133]
	v_pk_add_f32 v[122:123], v[122:123], v[134:135]
	v_pk_add_f32 v[124:125], v[124:125], v[136:137]
	v_pk_add_f32 v[118:119], v[118:119], v[138:139]
	v_pk_add_f32 v[120:121], v[120:121], v[140:141]
	v_pk_add_f32 v[114:115], v[114:115], v[142:143]
	v_pk_add_f32 v[116:117], v[116:117], v[144:145]
	v_pk_add_f32 v[110:111], v[110:111], v[130:131]
	v_pk_add_f32 v[112:113], v[112:113], v[132:133]
	v_pk_add_f32 v[106:107], v[106:107], v[134:135]
	v_pk_add_f32 v[108:109], v[108:109], v[136:137]
	v_pk_add_f32 v[102:103], v[102:103], v[138:139]
	v_pk_add_f32 v[104:105], v[104:105], v[140:141]
	v_pk_add_f32 v[98:99], v[98:99], v[142:143]
	v_pk_add_f32 v[100:101], v[100:101], v[144:145]
	v_pk_add_f32 v[94:95], v[94:95], v[130:131]
	v_pk_add_f32 v[96:97], v[96:97], v[132:133]
	v_pk_add_f32 v[90:91], v[90:91], v[134:135]
	v_pk_add_f32 v[92:93], v[92:93], v[136:137]
	v_pk_add_f32 v[86:87], v[86:87], v[138:139]
	v_pk_add_f32 v[88:89], v[88:89], v[140:141]
	v_pk_add_f32 v[82:83], v[82:83], v[142:143]
	v_pk_add_f32 v[84:85], v[84:85], v[144:145]
	v_pk_add_f32 v[78:79], v[78:79], v[130:131]
	v_pk_add_f32 v[80:81], v[80:81], v[132:133]
	v_pk_add_f32 v[74:75], v[74:75], v[134:135]
	v_pk_add_f32 v[76:77], v[76:77], v[136:137]
	v_pk_add_f32 v[70:71], v[70:71], v[138:139]
	v_pk_add_f32 v[72:73], v[72:73], v[140:141]
	v_pk_add_f32 v[66:67], v[66:67], v[142:143]
	v_pk_add_f32 v[68:69], v[68:69], v[144:145]
	v_pk_add_f32 v[62:63], v[62:63], v[130:131]
	v_pk_add_f32 v[64:65], v[64:65], v[132:133]
	v_pk_add_f32 v[58:59], v[58:59], v[134:135]
	v_pk_add_f32 v[60:61], v[60:61], v[136:137]
	v_pk_add_f32 v[54:55], v[54:55], v[138:139]
	v_pk_add_f32 v[56:57], v[56:57], v[140:141]
	v_pk_add_f32 v[50:51], v[50:51], v[142:143]
	v_pk_add_f32 v[52:53], v[52:53], v[144:145]
	v_pk_add_f32 v[46:47], v[46:47], v[130:131]
	v_pk_add_f32 v[48:49], v[48:49], v[132:133]
	v_pk_add_f32 v[42:43], v[42:43], v[134:135]
	v_pk_add_f32 v[44:45], v[44:45], v[136:137]
	v_pk_add_f32 v[38:39], v[38:39], v[138:139]
	v_pk_add_f32 v[40:41], v[40:41], v[140:141]
	v_pk_add_f32 v[34:35], v[34:35], v[142:143]
	v_pk_add_f32 v[36:37], v[36:37], v[144:145]
	v_pk_add_f32 v[30:31], v[30:31], v[130:131]
	v_pk_add_f32 v[32:33], v[32:33], v[132:133]
	v_pk_add_f32 v[26:27], v[26:27], v[134:135]
	v_pk_add_f32 v[28:29], v[28:29], v[136:137]
	v_pk_add_f32 v[22:23], v[22:23], v[138:139]
	v_pk_add_f32 v[24:25], v[24:25], v[140:141]
	v_pk_add_f32 v[18:19], v[18:19], v[142:143]
	v_pk_add_f32 v[20:21], v[20:21], v[144:145]
	v_pk_add_f32 v[14:15], v[14:15], v[130:131]
	v_pk_add_f32 v[16:17], v[16:17], v[132:133]
	v_pk_add_f32 v[10:11], v[10:11], v[134:135]
	v_pk_add_f32 v[12:13], v[12:13], v[136:137]
	v_pk_add_f32 v[6:7], v[6:7], v[138:139]
	v_pk_add_f32 v[8:9], v[8:9], v[140:141]
	v_pk_add_f32 v[2:3], v[2:3], v[142:143]
	v_pk_add_f32 v[4:5], v[4:5], v[144:145]
.Lres_nobias:
	s_nop 2
	global_load_dwordx4 v[216:219], v250, s[8:9] offset:0
	global_load_dwordx4 v[220:223], v250, s[8:9] offset:64
	global_load_dwordx4 v[240:243], v250, s[8:9] offset:512
	global_load_dwordx4 v[244:247], v250, s[8:9] offset:576
	v_readlane_b32 s3, v254, 61
	s_mov_b32 s2, -1
	s_cmp_eq_u32 s3, 8
	s_cselect_b32 s2, 2, s2
	s_cmp_eq_u32 s3, 10
	s_cselect_b32 s2, 4, s2
	s_cmp_eq_u32 s3, 17
	s_cselect_b32 s2, 6, s2
	s_cmp_eq_u32 s3, 19
	s_cselect_b32 s2, 8, s2
	s_cmp_eq_u32 s3, 21
	s_cselect_b32 s2, 9, s2
	s_cmp_eq_u32 s3, 25
	s_cselect_b32 s2, 10, s2
	s_cmp_eq_u32 s3, 27
	s_cselect_b32 s2, 12, s2
	s_cmp_eq_u32 s3, 29
	s_cselect_b32 s2, 13, s2
	s_cmp_eq_u32 s3, 32
	s_cselect_b32 s2, 14, s2
	s_cmp_eq_u32 s3, 34
	s_cselect_b32 s2, 99, s2
	s_mov_b32 s100, s2
	s_cmp_lt_i32 s2, 0
	s_cbranch_scc0 .Lrf_fused
	global_load_dwordx4 v[130:133], v248, s[10:11] offset:0
	s_add_u32 s14, s10, 0x10000
	s_addc_u32 s15, s11, 0
	global_load_dwordx4 v[134:137], v248, s[14:15] offset:0
	s_add_u32 s14, s10, 0x20000
	s_addc_u32 s15, s11, 0
	global_load_dwordx4 v[138:141], v248, s[14:15] offset:0
	s_add_u32 s14, s10, 0x30000
	s_addc_u32 s15, s11, 0
	global_load_dwordx4 v[142:145], v248, s[14:15] offset:0
	s_add_u32 s14, s10, 0x80000
	s_addc_u32 s15, s11, 0
	global_load_dwordx4 v[146:149], v248, s[14:15] offset:0
	s_add_u32 s14, s10, 0x90000
	s_addc_u32 s15, s11, 0
	global_load_dwordx4 v[150:153], v248, s[14:15] offset:0
	s_add_u32 s14, s10, 0xa0000
	s_addc_u32 s15, s11, 0
	global_load_dwordx4 v[154:157], v248, s[14:15] offset:0
	s_add_u32 s14, s10, 0xb0000
	s_addc_u32 s15, s11, 0
	global_load_dwordx4 v[158:161], v248, s[14:15] offset:0
	global_load_dwordx4 v[162:165], v248, s[10:11] offset:64
	s_add_u32 s14, s10, 0x10000
	s_addc_u32 s15, s11, 0
	global_load_dwordx4 v[188:191], v248, s[14:15] offset:64
	s_add_u32 s14, s10, 0x20000
	s_addc_u32 s15, s11, 0
	global_load_dwordx4 v[192:195], v248, s[14:15] offset:64
	s_add_u32 s14, s10, 0x30000
	s_addc_u32 s15, s11, 0
	global_load_dwordx4 v[196:199], v248, s[14:15] offset:64
	s_add_u32 s14, s10, 0x80000
	s_addc_u32 s15, s11, 0
	global_load_dwordx4 v[200:203], v248, s[14:15] offset:64
	s_add_u32 s14, s10, 0x90000
	s_addc_u32 s15, s11, 0
	global_load_dwordx4 v[204:207], v248, s[14:15] offset:64
	s_add_u32 s14, s10, 0xa0000
	s_addc_u32 s15, s11, 0
	global_load_dwordx4 v[208:211], v248, s[14:15] offset:64
	s_add_u32 s14, s10, 0xb0000
	s_addc_u32 s15, s11, 0
	global_load_dwordx4 v[212:215], v248, s[14:15] offset:64
	s_waitcnt vmcnt(12)
	v_pk_mul_f32 v[216:217], s[28:29], v[216:217]
	v_pk_mul_f32 v[218:219], s[28:29], v[218:219]
	v_pk_mul_f32 v[220:221], s[28:29], v[220:221]
	v_pk_mul_f32 v[222:223], s[28:29], v[222:223]
	v_pk_mul_f32 v[240:241], s[28:29], v[240:241]
	v_pk_mul_f32 v[242:243], s[28:29], v[242:243]
	v_pk_mul_f32 v[244:245], s[28:29], v[244:245]
	v_pk_mul_f32 v[246:247], s[28:29], v[246:247]
	v_pk_fma_f32 v[130:131], v[216:217], v[126:127], v[130:131]
	v_pk_fma_f32 v[132:133], v[218:219], v[128:129], v[132:133]
	v_pk_fma_f32 v[134:135], v[216:217], v[110:111], v[134:135]
	v_pk_fma_f32 v[136:137], v[218:219], v[112:113], v[136:137]
	v_pk_fma_f32 v[138:139], v[216:217], v[94:95], v[138:139]
	v_pk_fma_f32 v[140:141], v[218:219], v[96:97], v[140:141]
	v_pk_fma_f32 v[142:143], v[216:217], v[78:79], v[142:143]
	v_pk_fma_f32 v[144:145], v[218:219], v[80:81], v[144:145]
	global_store_dwordx4 v248, v[130:133], s[12:13] offset:0
	s_add_u32 s2, s12, 0x10000
	s_addc_u32 s3, s13, 0
	global_store_dwordx4 v248, v[134:137], s[2:3] offset:0
	s_add_u32 s2, s12, 0x20000
	s_addc_u32 s3, s13, 0
	global_store_dwordx4 v248, v[138:141], s[2:3] offset:0
	s_add_u32 s2, s12, 0x30000
	s_addc_u32 s3, s13, 0
	global_store_dwordx4 v248, v[142:145], s[2:3] offset:0
	global_load_dwordx4 v[130:133], v248, s[10:11] offset:512
	s_add_u32 s14, s10, 0x10000
	s_addc_u32 s15, s11, 0
	global_load_dwordx4 v[134:137], v248, s[14:15] offset:512
	s_add_u32 s14, s10, 0x20000
	s_addc_u32 s15, s11, 0
	global_load_dwordx4 v[138:141], v248, s[14:15] offset:512
	s_add_u32 s14, s10, 0x30000
	s_addc_u32 s15, s11, 0
	global_load_dwordx4 v[142:145], v248, s[14:15] offset:512
	s_waitcnt vmcnt(16)
	v_pk_fma_f32 v[146:147], v[216:217], v[62:63], v[146:147]
	v_pk_fma_f32 v[148:149], v[218:219], v[64:65], v[148:149]
	v_pk_fma_f32 v[150:151], v[216:217], v[46:47], v[150:151]
	v_pk_fma_f32 v[152:153], v[218:219], v[48:49], v[152:153]
	v_pk_fma_f32 v[154:155], v[216:217], v[30:31], v[154:155]
	v_pk_fma_f32 v[156:157], v[218:219], v[32:33], v[156:157]
	v_pk_fma_f32 v[158:159], v[216:217], v[14:15], v[158:159]
	v_pk_fma_f32 v[160:161], v[218:219], v[16:17], v[160:161]
	s_add_u32 s2, s12, 0x80000
	s_addc_u32 s3, s13, 0
	global_store_dwordx4 v248, v[146:149], s[2:3] offset:0
	s_add_u32 s2, s12, 0x90000
	s_addc_u32 s3, s13, 0
	global_store_dwordx4 v248, v[150:153], s[2:3] offset:0
	s_add_u32 s2, s12, 0xa0000
	s_addc_u32 s3, s13, 0
	global_store_dwordx4 v248, v[154:157], s[2:3] offset:0
	s_add_u32 s2, s12, 0xb0000
	s_addc_u32 s3, s13, 0
	global_store_dwordx4 v248, v[158:161], s[2:3] offset:0
	s_add_u32 s14, s10, 0x80000
	s_addc_u32 s15, s11, 0
	global_load_dwordx4 v[146:149], v248, s[14:15] offset:512
	s_add_u32 s14, s10, 0x90000
	s_addc_u32 s15, s11, 0
	global_load_dwordx4 v[150:153], v248, s[14:15] offset:512
	s_add_u32 s14, s10, 0xa0000
	s_addc_u32 s15, s11, 0
	global_load_dwordx4 v[154:157], v248, s[14:15] offset:512
	s_add_u32 s14, s10, 0xb0000
	s_addc_u32 s15, s11, 0
	global_load_dwordx4 v[158:161], v248, s[14:15] offset:512
	s_waitcnt vmcnt(20)
	v_pk_fma_f32 v[162:163], v[220:221], v[122:123], v[162:163]
	v_pk_fma_f32 v[164:165], v[222:223], v[124:125], v[164:165]
	v_pk_fma_f32 v[188:189], v[220:221], v[106:107], v[188:189]
	v_pk_fma_f32 v[190:191], v[222:223], v[108:109], v[190:191]
	v_pk_fma_f32 v[192:193], v[220:221], v[90:91], v[192:193]
	v_pk_fma_f32 v[194:195], v[222:223], v[92:93], v[194:195]
	v_pk_fma_f32 v[196:197], v[220:221], v[74:75], v[196:197]
	v_pk_fma_f32 v[198:199], v[222:223], v[76:77], v[198:199]
	global_store_dwordx4 v248, v[162:165], s[12:13] offset:64
	s_add_u32 s2, s12, 0x10000
	s_addc_u32 s3, s13, 0
	global_store_dwordx4 v248, v[188:191], s[2:3] offset:64
	s_add_u32 s2, s12, 0x20000
	s_addc_u32 s3, s13, 0
	global_store_dwordx4 v248, v[192:195], s[2:3] offset:64
	s_add_u32 s2, s12, 0x30000
	s_addc_u32 s3, s13, 0
	global_store_dwordx4 v248, v[196:199], s[2:3] offset:64
	global_load_dwordx4 v[162:165], v248, s[10:11] offset:576
	s_add_u32 s14, s10, 0x10000
	s_addc_u32 s15, s11, 0
	global_load_dwordx4 v[188:191], v248, s[14:15] offset:576
	s_add_u32 s14, s10, 0x20000
	s_addc_u32 s15, s11, 0
	global_load_dwordx4 v[192:195], v248, s[14:15] offset:576
	s_add_u32 s14, s10, 0x30000
	s_addc_u32 s15, s11, 0
	global_load_dwordx4 v[196:199], v248, s[14:15] offset:576
	s_waitcnt vmcnt(24)
	v_pk_fma_f32 v[200:201], v[220:221], v[58:59], v[200:201]
	v_pk_fma_f32 v[202:203], v[222:223], v[60:61], v[202:203]
	v_pk_fma_f32 v[204:205], v[220:221], v[42:43], v[204:205]
	v_pk_fma_f32 v[206:207], v[222:223], v[44:45], v[206:207]
	v_pk_fma_f32 v[208:209], v[220:221], v[26:27], v[208:209]
	v_pk_fma_f32 v[210:211], v[222:223], v[28:29], v[210:211]
	v_pk_fma_f32 v[212:213], v[220:221], v[10:11], v[212:213]
	v_pk_fma_f32 v[214:215], v[222:223], v[12:13], v[214:215]
	s_add_u32 s2, s12, 0x80000
	s_addc_u32 s3, s13, 0
	global_store_dwordx4 v248, v[200:203], s[2:3] offset:64
	s_add_u32 s2, s12, 0x90000
	s_addc_u32 s3, s13, 0
	global_store_dwordx4 v248, v[204:207], s[2:3] offset:64
	s_add_u32 s2, s12, 0xa0000
	s_addc_u32 s3, s13, 0
	global_store_dwordx4 v248, v[208:211], s[2:3] offset:64
	s_add_u32 s2, s12, 0xb0000
	s_addc_u32 s3, s13, 0
	global_store_dwordx4 v248, v[212:215], s[2:3] offset:64
	s_add_u32 s14, s10, 0x80000
	s_addc_u32 s15, s11, 0
	global_load_dwordx4 v[200:203], v248, s[14:15] offset:576
	s_add_u32 s14, s10, 0x90000
	s_addc_u32 s15, s11, 0
	global_load_dwordx4 v[204:207], v248, s[14:15] offset:576
	s_add_u32 s14, s10, 0xa0000
	s_addc_u32 s15, s11, 0
	global_load_dwordx4 v[208:211], v248, s[14:15] offset:576
	s_add_u32 s14, s10, 0xb0000
	s_addc_u32 s15, s11, 0
	global_load_dwordx4 v[212:215], v248, s[14:15] offset:576
	s_waitcnt vmcnt(24)
	v_pk_fma_f32 v[130:131], v[240:241], v[118:119], v[130:131]
	v_pk_fma_f32 v[132:133], v[242:243], v[120:121], v[132:133]
	v_pk_fma_f32 v[134:135], v[240:241], v[102:103], v[134:135]
	v_pk_fma_f32 v[136:137], v[242:243], v[104:105], v[136:137]
	v_pk_fma_f32 v[138:139], v[240:241], v[86:87], v[138:139]
	v_pk_fma_f32 v[140:141], v[242:243], v[88:89], v[140:141]
	v_pk_fma_f32 v[142:143], v[240:241], v[70:71], v[142:143]
	v_pk_fma_f32 v[144:145], v[242:243], v[72:73], v[144:145]
	global_store_dwordx4 v248, v[130:133], s[12:13] offset:512
	s_add_u32 s2, s12, 0x10000
	s_addc_u32 s3, s13, 0
	global_store_dwordx4 v248, v[134:137], s[2:3] offset:512
	s_add_u32 s2, s12, 0x20000
	s_addc_u32 s3, s13, 0
	global_store_dwordx4 v248, v[138:141], s[2:3] offset:512
	s_add_u32 s2, s12, 0x30000
	s_addc_u32 s3, s13, 0
	global_store_dwordx4 v248, v[142:145], s[2:3] offset:512
	s_waitcnt vmcnt(20)
	v_pk_fma_f32 v[146:147], v[240:241], v[54:55], v[146:147]
	v_pk_fma_f32 v[148:149], v[242:243], v[56:57], v[148:149]
	v_pk_fma_f32 v[150:151], v[240:241], v[38:39], v[150:151]
	v_pk_fma_f32 v[152:153], v[242:243], v[40:41], v[152:153]
	v_pk_fma_f32 v[154:155], v[240:241], v[22:23], v[154:155]
	v_pk_fma_f32 v[156:157], v[242:243], v[24:25], v[156:157]
	v_pk_fma_f32 v[158:159], v[240:241], v[6:7], v[158:159]
	v_pk_fma_f32 v[160:161], v[242:243], v[8:9], v[160:161]
	s_add_u32 s2, s12, 0x80000
	s_addc_u32 s3, s13, 0
	global_store_dwordx4 v248, v[146:149], s[2:3] offset:512
	s_add_u32 s2, s12, 0x90000
	s_addc_u32 s3, s13, 0
	global_store_dwordx4 v248, v[150:153], s[2:3] offset:512
	s_add_u32 s2, s12, 0xa0000
	s_addc_u32 s3, s13, 0
	global_store_dwordx4 v248, v[154:157], s[2:3] offset:512
	s_add_u32 s2, s12, 0xb0000
	s_addc_u32 s3, s13, 0
	global_store_dwordx4 v248, v[158:161], s[2:3] offset:512
	s_waitcnt vmcnt(16)
	v_pk_fma_f32 v[162:163], v[244:245], v[114:115], v[162:163]
	v_pk_fma_f32 v[164:165], v[246:247], v[116:117], v[164:165]
	v_pk_fma_f32 v[188:189], v[244:245], v[98:99], v[188:189]
	v_pk_fma_f32 v[190:191], v[246:247], v[100:101], v[190:191]
	v_pk_fma_f32 v[192:193], v[244:245], v[82:83], v[192:193]
	v_pk_fma_f32 v[194:195], v[246:247], v[84:85], v[194:195]
	v_pk_fma_f32 v[196:197], v[244:245], v[66:67], v[196:197]
	v_pk_fma_f32 v[198:199], v[246:247], v[68:69], v[198:199]
	global_store_dwordx4 v248, v[162:165], s[12:13] offset:576
	s_add_u32 s2, s12, 0x10000
	s_addc_u32 s3, s13, 0
	global_store_dwordx4 v248, v[188:191], s[2:3] offset:576
	s_add_u32 s2, s12, 0x20000
	s_addc_u32 s3, s13, 0
	global_store_dwordx4 v248, v[192:195], s[2:3] offset:576
	s_add_u32 s2, s12, 0x30000
	s_addc_u32 s3, s13, 0
	global_store_dwordx4 v248, v[196:199], s[2:3] offset:576
	s_waitcnt vmcnt(12)
	v_pk_fma_f32 v[200:201], v[244:245], v[50:51], v[200:201]
	v_pk_fma_f32 v[202:203], v[246:247], v[52:53], v[202:203]
	v_pk_fma_f32 v[204:205], v[244:245], v[34:35], v[204:205]
	v_pk_fma_f32 v[206:207], v[246:247], v[36:37], v[206:207]
	v_pk_fma_f32 v[208:209], v[244:245], v[18:19], v[208:209]
	v_pk_fma_f32 v[210:211], v[246:247], v[20:21], v[210:211]
	v_pk_fma_f32 v[212:213], v[244:245], v[2:3], v[212:213]
	v_pk_fma_f32 v[214:215], v[246:247], v[4:5], v[214:215]
	s_add_u32 s2, s12, 0x80000
	s_addc_u32 s3, s13, 0
	global_store_dwordx4 v248, v[200:203], s[2:3] offset:576
	s_add_u32 s2, s12, 0x90000
	s_addc_u32 s3, s13, 0
	global_store_dwordx4 v248, v[204:207], s[2:3] offset:576
	s_add_u32 s2, s12, 0xa0000
	s_addc_u32 s3, s13, 0
	global_store_dwordx4 v248, v[208:211], s[2:3] offset:576
	s_add_u32 s2, s12, 0xb0000
	s_addc_u32 s3, s13, 0
	global_store_dwordx4 v248, v[212:215], s[2:3] offset:576
	s_branch .LBB0_561

.Lrf_nopub:
	s_waitcnt vmcnt(0)
	v_readlane_b32 s8, v254, 61
	s_cmp_eq_u32 s8, 34
	s_cbranch_scc1 .Lrf_j1
	v_add_f32_e32 v146, 1.0, v146
	v_add_f32_e32 v147, 1.0, v147
	v_add_f32_e32 v148, 1.0, v148
	v_add_f32_e32 v149, 1.0, v149
	v_add_f32_e32 v150, 1.0, v150
	v_add_f32_e32 v151, 1.0, v151
	v_add_f32_e32 v152, 1.0, v152
	v_add_f32_e32 v153, 1.0, v153
	v_add_f32_e32 v154, 1.0, v154
	v_add_f32_e32 v155, 1.0, v155
	v_add_f32_e32 v156, 1.0, v156
	v_add_f32_e32 v157, 1.0, v157
	v_add_f32_e32 v158, 1.0, v158
	v_add_f32_e32 v159, 1.0, v159
	v_add_f32_e32 v160, 1.0, v160
	v_add_f32_e32 v161, 1.0, v161
	v_mul_f32_e32 v146, v130, v146
	v_mul_f32_e32 v147, v131, v147
	v_mul_f32_e32 v148, v132, v148
	v_mul_f32_e32 v149, v133, v149
	v_mul_f32_e32 v150, v134, v150
	v_mul_f32_e32 v151, v135, v151
	v_mul_f32_e32 v152, v136, v152
	v_mul_f32_e32 v153, v137, v153
	v_mul_f32_e32 v154, v138, v154
	v_mul_f32_e32 v155, v139, v155
	v_mul_f32_e32 v156, v140, v156
	v_mul_f32_e32 v157, v141, v157
	v_mul_f32_e32 v158, v142, v158
	v_mul_f32_e32 v159, v143, v159
	v_mul_f32_e32 v160, v144, v160
	v_mul_f32_e32 v161, v145, v161

.Lrf_bar:
	s_barrier
	global_load_dwordx4 v[200:203], v253, s[10:11] offset:0
	global_load_dwordx4 v[204:207], v253, s[10:11] offset:256
	global_load_dwordx4 v[208:211], v253, s[10:11] offset:512
	global_load_dwordx4 v[212:215], v253, s[10:11] offset:768
	global_load_dwordx4 v[216:219], v253, s[10:11] offset:2048
	global_load_dwordx4 v[220:223], v253, s[10:11] offset:2304
	global_load_dwordx4 v[240:243], v253, s[10:11] offset:2560
	global_load_dwordx4 v[244:247], v253, s[10:11] offset:2816
	v_lshl_add_u32 v251, v236, 2, s68
	v_lshlrev_b32_e32 v251, 1, v251
	v_add_u32_e32 v249, s67, v235
	v_mul_u32_u24_e32 v249, 0x210, v249
	v_add_u32_e32 v251, v251, v249
	v_add_u32_e32 v252, 0x10800, v251
	s_mov_b32 s2, 0x3a800000
	s_waitcnt vmcnt(7)
	v_add_f32_e32 v200, v200, v201
	v_add_f32_e32 v202, v202, v203
	v_add_f32_e32 v200, v200, v202
	v_fma_f32 v200, v200, s2, v167
	v_rsq_f32_e32 v200, v200
	s_waitcnt vmcnt(6)
	v_add_f32_e32 v204, v204, v205
	v_add_f32_e32 v206, v206, v207
	v_add_f32_e32 v204, v204, v206
	v_fma_f32 v204, v204, s2, v167
	v_rsq_f32_e32 v204, v204
	s_waitcnt vmcnt(5)
	v_add_f32_e32 v208, v208, v209
	v_add_f32_e32 v210, v210, v211
	v_add_f32_e32 v208, v208, v210
	v_fma_f32 v208, v208, s2, v167
	v_rsq_f32_e32 v208, v208
	s_waitcnt vmcnt(4)
	v_add_f32_e32 v212, v212, v213
	v_add_f32_e32 v214, v214, v215
	v_add_f32_e32 v212, v212, v214
	v_fma_f32 v212, v212, s2, v167
	v_rsq_f32_e32 v212, v212
	s_waitcnt vmcnt(3)
	v_add_f32_e32 v216, v216, v217
	v_add_f32_e32 v218, v218, v219
	v_add_f32_e32 v216, v216, v218
	v_fma_f32 v216, v216, s2, v167
	v_rsq_f32_e32 v216, v216
	s_waitcnt vmcnt(2)
	v_add_f32_e32 v220, v220, v221
	v_add_f32_e32 v222, v222, v223
	v_add_f32_e32 v220, v220, v222
	v_fma_f32 v220, v220, s2, v167
	v_rsq_f32_e32 v220, v220
	s_waitcnt vmcnt(1)
	v_add_f32_e32 v240, v240, v241
	v_add_f32_e32 v242, v242, v243
	v_add_f32_e32 v240, v240, v242
	v_fma_f32 v240, v240, s2, v167
	v_rsq_f32_e32 v240, v240
	s_waitcnt vmcnt(0)
	v_add_f32_e32 v244, v244, v245
	v_add_f32_e32 v246, v246, v247
	v_add_f32_e32 v244, v244, v246
	v_fma_f32 v244, v244, s2, v167
	v_rsq_f32_e32 v244, v244
	s_nop 0
	v_readlane_b32 s8, v254, 61
	s_cmp_eq_u32 s8, 34
	s_cbranch_scc1 .Lrf_fin2
	global_store_dwordx4 v248, v[126:129], s[100:101] offset:0
	global_store_dwordx4 v248, v[122:125], s[100:101] offset:64
	global_store_dwordx4 v248, v[118:121], s[100:101] offset:512
	global_store_dwordx4 v248, v[114:117], s[100:101] offset:576
	s_nop 1
	v_mul_f32_e32 v126, v126, v200
	v_mul_f32_e32 v127, v127, v200
	v_mul_f32_e32 v128, v128, v200
	v_mul_f32_e32 v129, v129, v200
	v_fma_f32 v126, v126, v146, v162
	v_fma_f32 v127, v127, v147, v163
	v_fma_f32 v128, v128, v148, v164
	v_fma_f32 v129, v129, v149, v165
	v_cvt_pk_bf16_f32 v126, v126, v127
	v_cvt_pk_bf16_f32 v127, v128, v129
	v_mul_f32_e32 v122, v122, v200
	v_mul_f32_e32 v123, v123, v200
	v_mul_f32_e32 v124, v124, v200
	v_mul_f32_e32 v125, v125, v200
	v_fma_f32 v122, v122, v150, v188
	v_fma_f32 v123, v123, v151, v189
	v_fma_f32 v124, v124, v152, v190
	v_fma_f32 v125, v125, v153, v191
	v_cvt_pk_bf16_f32 v122, v122, v123
	v_cvt_pk_bf16_f32 v123, v124, v125
	v_mul_f32_e32 v118, v118, v200
	v_mul_f32_e32 v119, v119, v200
	v_mul_f32_e32 v120, v120, v200
	v_mul_f32_e32 v121, v121, v200
	v_fma_f32 v118, v118, v154, v192
	v_fma_f32 v119, v119, v155, v193
	v_fma_f32 v120, v120, v156, v194
	v_fma_f32 v121, v121, v157, v195
	v_cvt_pk_bf16_f32 v118, v118, v119
	v_cvt_pk_bf16_f32 v119, v120, v121
	v_mul_f32_e32 v114, v114, v200
	v_mul_f32_e32 v115, v115, v200
	v_mul_f32_e32 v116, v116, v200
	v_mul_f32_e32 v117, v117, v200
	v_fma_f32 v114, v114, v158, v196
	v_fma_f32 v115, v115, v159, v197
	v_fma_f32 v116, v116, v160, v198
	v_fma_f32 v117, v117, v161, v199
	v_cvt_pk_bf16_f32 v114, v114, v115
	v_cvt_pk_bf16_f32 v115, v116, v117
	ds_write_b64 v251, v[126:127] offset:0
	ds_write_b64 v251, v[122:123] offset:32
	ds_write_b64 v251, v[118:119] offset:256
	ds_write_b64 v251, v[114:115] offset:288
	s_add_u32 s8, s100, 0x10000
	s_addc_u32 s9, s101, 0
	global_store_dwordx4 v248, v[110:113], s[8:9] offset:0
	global_store_dwordx4 v248, v[106:109], s[8:9] offset:64
	global_store_dwordx4 v248, v[102:105], s[8:9] offset:512
	global_store_dwordx4 v248, v[98:101], s[8:9] offset:576
	s_nop 1
	v_mul_f32_e32 v110, v110, v204
	v_mul_f32_e32 v111, v111, v204
	v_mul_f32_e32 v112, v112, v204
	v_mul_f32_e32 v113, v113, v204
	v_fma_f32 v110, v110, v146, v162
	v_fma_f32 v111, v111, v147, v163
	v_fma_f32 v112, v112, v148, v164
	v_fma_f32 v113, v113, v149, v165
	v_cvt_pk_bf16_f32 v110, v110, v111
	v_cvt_pk_bf16_f32 v111, v112, v113
	v_mul_f32_e32 v106, v106, v204
	v_mul_f32_e32 v107, v107, v204
	v_mul_f32_e32 v108, v108, v204
	v_mul_f32_e32 v109, v109, v204
	v_fma_f32 v106, v106, v150, v188
	v_fma_f32 v107, v107, v151, v189
	v_fma_f32 v108, v108, v152, v190
	v_fma_f32 v109, v109, v153, v191
	v_cvt_pk_bf16_f32 v106, v106, v107
	v_cvt_pk_bf16_f32 v107, v108, v109
	v_mul_f32_e32 v102, v102, v204
	v_mul_f32_e32 v103, v103, v204
	v_mul_f32_e32 v104, v104, v204
	v_mul_f32_e32 v105, v105, v204
	v_fma_f32 v102, v102, v154, v192
	v_fma_f32 v103, v103, v155, v193
	v_fma_f32 v104, v104, v156, v194
	v_fma_f32 v105, v105, v157, v195
	v_cvt_pk_bf16_f32 v102, v102, v103
	v_cvt_pk_bf16_f32 v103, v104, v105
	v_mul_f32_e32 v98, v98, v204
	v_mul_f32_e32 v99, v99, v204
	v_mul_f32_e32 v100, v100, v204
	v_mul_f32_e32 v101, v101, v204
	v_fma_f32 v98, v98, v158, v196
	v_fma_f32 v99, v99, v159, v197
	v_fma_f32 v100, v100, v160, v198
	v_fma_f32 v101, v101, v161, v199
	v_cvt_pk_bf16_f32 v98, v98, v99
	v_cvt_pk_bf16_f32 v99, v100, v101
	ds_write_b64 v251, v[110:111] offset:8448
	ds_write_b64 v251, v[106:107] offset:8480
	ds_write_b64 v251, v[102:103] offset:8704
	ds_write_b64 v251, v[98:99] offset:8736
	s_add_u32 s8, s100, 0x20000
	s_addc_u32 s9, s101, 0
	global_store_dwordx4 v248, v[94:97], s[8:9] offset:0
	global_store_dwordx4 v248, v[90:93], s[8:9] offset:64
	global_store_dwordx4 v248, v[86:89], s[8:9] offset:512
	global_store_dwordx4 v248, v[82:85], s[8:9] offset:576
	s_nop 1
	v_mul_f32_e32 v94, v94, v208
	v_mul_f32_e32 v95, v95, v208
	v_mul_f32_e32 v96, v96, v208
	v_mul_f32_e32 v97, v97, v208
	v_fma_f32 v94, v94, v146, v162
	v_fma_f32 v95, v95, v147, v163
	v_fma_f32 v96, v96, v148, v164
	v_fma_f32 v97, v97, v149, v165
	v_cvt_pk_bf16_f32 v94, v94, v95
	v_cvt_pk_bf16_f32 v95, v96, v97
	v_mul_f32_e32 v90, v90, v208
	v_mul_f32_e32 v91, v91, v208
	v_mul_f32_e32 v92, v92, v208
	v_mul_f32_e32 v93, v93, v208
	v_fma_f32 v90, v90, v150, v188
	v_fma_f32 v91, v91, v151, v189
	v_fma_f32 v92, v92, v152, v190
	v_fma_f32 v93, v93, v153, v191
	v_cvt_pk_bf16_f32 v90, v90, v91
	v_cvt_pk_bf16_f32 v91, v92, v93
	v_mul_f32_e32 v86, v86, v208
	v_mul_f32_e32 v87, v87, v208
	v_mul_f32_e32 v88, v88, v208
	v_mul_f32_e32 v89, v89, v208
	v_fma_f32 v86, v86, v154, v192
	v_fma_f32 v87, v87, v155, v193
	v_fma_f32 v88, v88, v156, v194
	v_fma_f32 v89, v89, v157, v195
	v_cvt_pk_bf16_f32 v86, v86, v87
	v_cvt_pk_bf16_f32 v87, v88, v89
	v_mul_f32_e32 v82, v82, v208
	v_mul_f32_e32 v83, v83, v208
	v_mul_f32_e32 v84, v84, v208
	v_mul_f32_e32 v85, v85, v208
	v_fma_f32 v82, v82, v158, v196
	v_fma_f32 v83, v83, v159, v197
	v_fma_f32 v84, v84, v160, v198
	v_fma_f32 v85, v85, v161, v199
	v_cvt_pk_bf16_f32 v82, v82, v83
	v_cvt_pk_bf16_f32 v83, v84, v85
	ds_write_b64 v251, v[94:95] offset:16896
	ds_write_b64 v251, v[90:91] offset:16928
	ds_write_b64 v251, v[86:87] offset:17152
	ds_write_b64 v251, v[82:83] offset:17184
	s_add_u32 s8, s100, 0x30000
	s_addc_u32 s9, s101, 0
	global_store_dwordx4 v248, v[78:81], s[8:9] offset:0
	global_store_dwordx4 v248, v[74:77], s[8:9] offset:64
	global_store_dwordx4 v248, v[70:73], s[8:9] offset:512
	global_store_dwordx4 v248, v[66:69], s[8:9] offset:576
	s_nop 1
	v_mul_f32_e32 v78, v78, v212
	v_mul_f32_e32 v79, v79, v212
	v_mul_f32_e32 v80, v80, v212
	v_mul_f32_e32 v81, v81, v212
	v_fma_f32 v78, v78, v146, v162
	v_fma_f32 v79, v79, v147, v163
	v_fma_f32 v80, v80, v148, v164
	v_fma_f32 v81, v81, v149, v165
	v_cvt_pk_bf16_f32 v78, v78, v79
	v_cvt_pk_bf16_f32 v79, v80, v81
	v_mul_f32_e32 v74, v74, v212
	v_mul_f32_e32 v75, v75, v212
	v_mul_f32_e32 v76, v76, v212
	v_mul_f32_e32 v77, v77, v212
	v_fma_f32 v74, v74, v150, v188
	v_fma_f32 v75, v75, v151, v189
	v_fma_f32 v76, v76, v152, v190
	v_fma_f32 v77, v77, v153, v191
	v_cvt_pk_bf16_f32 v74, v74, v75
	v_cvt_pk_bf16_f32 v75, v76, v77
	v_mul_f32_e32 v70, v70, v212
	v_mul_f32_e32 v71, v71, v212
	v_mul_f32_e32 v72, v72, v212
	v_mul_f32_e32 v73, v73, v212
	v_fma_f32 v70, v70, v154, v192
	v_fma_f32 v71, v71, v155, v193
	v_fma_f32 v72, v72, v156, v194
	v_fma_f32 v73, v73, v157, v195
	v_cvt_pk_bf16_f32 v70, v70, v71
	v_cvt_pk_bf16_f32 v71, v72, v73
	v_mul_f32_e32 v66, v66, v212
	v_mul_f32_e32 v67, v67, v212
	v_mul_f32_e32 v68, v68, v212
	v_mul_f32_e32 v69, v69, v212
	v_fma_f32 v66, v66, v158, v196
	v_fma_f32 v67, v67, v159, v197
	v_fma_f32 v68, v68, v160, v198
	v_fma_f32 v69, v69, v161, v199
	v_cvt_pk_bf16_f32 v66, v66, v67
	v_cvt_pk_bf16_f32 v67, v68, v69
	ds_write_b64 v251, v[78:79] offset:25344
	ds_write_b64 v251, v[74:75] offset:25376
	ds_write_b64 v251, v[70:71] offset:25600
	ds_write_b64 v251, v[66:67] offset:25632
	s_add_u32 s8, s100, 0x80000
	s_addc_u32 s9, s101, 0
	global_store_dwordx4 v248, v[62:65], s[8:9] offset:0
	global_store_dwordx4 v248, v[58:61], s[8:9] offset:64
	global_store_dwordx4 v248, v[54:57], s[8:9] offset:512
	global_store_dwordx4 v248, v[50:53], s[8:9] offset:576
	s_nop 1
	v_mul_f32_e32 v62, v62, v216
	v_mul_f32_e32 v63, v63, v216
	v_mul_f32_e32 v64, v64, v216
	v_mul_f32_e32 v65, v65, v216
	v_fma_f32 v62, v62, v146, v162
	v_fma_f32 v63, v63, v147, v163
	v_fma_f32 v64, v64, v148, v164
	v_fma_f32 v65, v65, v149, v165
	v_cvt_pk_bf16_f32 v62, v62, v63
	v_cvt_pk_bf16_f32 v63, v64, v65
	v_mul_f32_e32 v58, v58, v216
	v_mul_f32_e32 v59, v59, v216
	v_mul_f32_e32 v60, v60, v216
	v_mul_f32_e32 v61, v61, v216
	v_fma_f32 v58, v58, v150, v188
	v_fma_f32 v59, v59, v151, v189
	v_fma_f32 v60, v60, v152, v190
	v_fma_f32 v61, v61, v153, v191
	v_cvt_pk_bf16_f32 v58, v58, v59
	v_cvt_pk_bf16_f32 v59, v60, v61
	v_mul_f32_e32 v54, v54, v216
	v_mul_f32_e32 v55, v55, v216
	v_mul_f32_e32 v56, v56, v216
	v_mul_f32_e32 v57, v57, v216
	v_fma_f32 v54, v54, v154, v192
	v_fma_f32 v55, v55, v155, v193
	v_fma_f32 v56, v56, v156, v194
	v_fma_f32 v57, v57, v157, v195
	v_cvt_pk_bf16_f32 v54, v54, v55
	v_cvt_pk_bf16_f32 v55, v56, v57
	v_mul_f32_e32 v50, v50, v216
	v_mul_f32_e32 v51, v51, v216
	v_mul_f32_e32 v52, v52, v216
	v_mul_f32_e32 v53, v53, v216
	v_fma_f32 v50, v50, v158, v196
	v_fma_f32 v51, v51, v159, v197
	v_fma_f32 v52, v52, v160, v198
	v_fma_f32 v53, v53, v161, v199
	v_cvt_pk_bf16_f32 v50, v50, v51
	v_cvt_pk_bf16_f32 v51, v52, v53
	ds_write_b64 v252, v[62:63] offset:0
	ds_write_b64 v252, v[58:59] offset:32
	ds_write_b64 v252, v[54:55] offset:256
	ds_write_b64 v252, v[50:51] offset:288
	s_add_u32 s8, s100, 0x90000
	s_addc_u32 s9, s101, 0
	global_store_dwordx4 v248, v[46:49], s[8:9] offset:0
	global_store_dwordx4 v248, v[42:45], s[8:9] offset:64
	global_store_dwordx4 v248, v[38:41], s[8:9] offset:512
	global_store_dwordx4 v248, v[34:37], s[8:9] offset:576
	s_nop 1
	v_mul_f32_e32 v46, v46, v220
	v_mul_f32_e32 v47, v47, v220
	v_mul_f32_e32 v48, v48, v220
	v_mul_f32_e32 v49, v49, v220
	v_fma_f32 v46, v46, v146, v162
	v_fma_f32 v47, v47, v147, v163
	v_fma_f32 v48, v48, v148, v164
	v_fma_f32 v49, v49, v149, v165
	v_cvt_pk_bf16_f32 v46, v46, v47
	v_cvt_pk_bf16_f32 v47, v48, v49
	v_mul_f32_e32 v42, v42, v220
	v_mul_f32_e32 v43, v43, v220
	v_mul_f32_e32 v44, v44, v220
	v_mul_f32_e32 v45, v45, v220
	v_fma_f32 v42, v42, v150, v188
	v_fma_f32 v43, v43, v151, v189
	v_fma_f32 v44, v44, v152, v190
	v_fma_f32 v45, v45, v153, v191
	v_cvt_pk_bf16_f32 v42, v42, v43
	v_cvt_pk_bf16_f32 v43, v44, v45
	v_mul_f32_e32 v38, v38, v220
	v_mul_f32_e32 v39, v39, v220
	v_mul_f32_e32 v40, v40, v220
	v_mul_f32_e32 v41, v41, v220
	v_fma_f32 v38, v38, v154, v192
	v_fma_f32 v39, v39, v155, v193
	v_fma_f32 v40, v40, v156, v194
	v_fma_f32 v41, v41, v157, v195
	v_cvt_pk_bf16_f32 v38, v38, v39
	v_cvt_pk_bf16_f32 v39, v40, v41
	v_mul_f32_e32 v34, v34, v220
	v_mul_f32_e32 v35, v35, v220
	v_mul_f32_e32 v36, v36, v220
	v_mul_f32_e32 v37, v37, v220
	v_fma_f32 v34, v34, v158, v196
	v_fma_f32 v35, v35, v159, v197
	v_fma_f32 v36, v36, v160, v198
	v_fma_f32 v37, v37, v161, v199
	v_cvt_pk_bf16_f32 v34, v34, v35
	v_cvt_pk_bf16_f32 v35, v36, v37
	ds_write_b64 v252, v[46:47] offset:8448
	ds_write_b64 v252, v[42:43] offset:8480
	ds_write_b64 v252, v[38:39] offset:8704
	ds_write_b64 v252, v[34:35] offset:8736
	s_add_u32 s8, s100, 0xa0000
	s_addc_u32 s9, s101, 0
	global_store_dwordx4 v248, v[30:33], s[8:9] offset:0
	global_store_dwordx4 v248, v[26:29], s[8:9] offset:64
	global_store_dwordx4 v248, v[22:25], s[8:9] offset:512
	global_store_dwordx4 v248, v[18:21], s[8:9] offset:576
	s_nop 1
	v_mul_f32_e32 v30, v30, v240
	v_mul_f32_e32 v31, v31, v240
	v_mul_f32_e32 v32, v32, v240
	v_mul_f32_e32 v33, v33, v240
	v_fma_f32 v30, v30, v146, v162
	v_fma_f32 v31, v31, v147, v163
	v_fma_f32 v32, v32, v148, v164
	v_fma_f32 v33, v33, v149, v165
	v_cvt_pk_bf16_f32 v30, v30, v31
	v_cvt_pk_bf16_f32 v31, v32, v33
	v_mul_f32_e32 v26, v26, v240
	v_mul_f32_e32 v27, v27, v240
	v_mul_f32_e32 v28, v28, v240
	v_mul_f32_e32 v29, v29, v240
	v_fma_f32 v26, v26, v150, v188
	v_fma_f32 v27, v27, v151, v189
	v_fma_f32 v28, v28, v152, v190
	v_fma_f32 v29, v29, v153, v191
	v_cvt_pk_bf16_f32 v26, v26, v27
	v_cvt_pk_bf16_f32 v27, v28, v29
	v_mul_f32_e32 v22, v22, v240
	v_mul_f32_e32 v23, v23, v240
	v_mul_f32_e32 v24, v24, v240
	v_mul_f32_e32 v25, v25, v240
	v_fma_f32 v22, v22, v154, v192
	v_fma_f32 v23, v23, v155, v193
	v_fma_f32 v24, v24, v156, v194
	v_fma_f32 v25, v25, v157, v195
	v_cvt_pk_bf16_f32 v22, v22, v23
	v_cvt_pk_bf16_f32 v23, v24, v25
	v_mul_f32_e32 v18, v18, v240
	v_mul_f32_e32 v19, v19, v240
	v_mul_f32_e32 v20, v20, v240
	v_mul_f32_e32 v21, v21, v240
	v_fma_f32 v18, v18, v158, v196
	v_fma_f32 v19, v19, v159, v197
	v_fma_f32 v20, v20, v160, v198
	v_fma_f32 v21, v21, v161, v199
	v_cvt_pk_bf16_f32 v18, v18, v19
	v_cvt_pk_bf16_f32 v19, v20, v21
	ds_write_b64 v252, v[30:31] offset:16896
	ds_write_b64 v252, v[26:27] offset:16928
	ds_write_b64 v252, v[22:23] offset:17152
	ds_write_b64 v252, v[18:19] offset:17184
	s_add_u32 s8, s100, 0xb0000
	s_addc_u32 s9, s101, 0
	global_store_dwordx4 v248, v[14:17], s[8:9] offset:0
	global_store_dwordx4 v248, v[10:13], s[8:9] offset:64
	global_store_dwordx4 v248, v[6:9], s[8:9] offset:512
	global_store_dwordx4 v248, v[2:5], s[8:9] offset:576
	s_nop 1
	v_mul_f32_e32 v14, v14, v244
	v_mul_f32_e32 v15, v15, v244
	v_mul_f32_e32 v16, v16, v244
	v_mul_f32_e32 v17, v17, v244
	v_fma_f32 v14, v14, v146, v162
	v_fma_f32 v15, v15, v147, v163
	v_fma_f32 v16, v16, v148, v164
	v_fma_f32 v17, v17, v149, v165
	v_cvt_pk_bf16_f32 v14, v14, v15
	v_cvt_pk_bf16_f32 v15, v16, v17
	v_mul_f32_e32 v10, v10, v244
	v_mul_f32_e32 v11, v11, v244
	v_mul_f32_e32 v12, v12, v244
	v_mul_f32_e32 v13, v13, v244
	v_fma_f32 v10, v10, v150, v188
	v_fma_f32 v11, v11, v151, v189
	v_fma_f32 v12, v12, v152, v190
	v_fma_f32 v13, v13, v153, v191
	v_cvt_pk_bf16_f32 v10, v10, v11
	v_cvt_pk_bf16_f32 v11, v12, v13
	v_mul_f32_e32 v6, v6, v244
	v_mul_f32_e32 v7, v7, v244
	v_mul_f32_e32 v8, v8, v244
	v_mul_f32_e32 v9, v9, v244
	v_fma_f32 v6, v6, v154, v192
	v_fma_f32 v7, v7, v155, v193
	v_fma_f32 v8, v8, v156, v194
	v_fma_f32 v9, v9, v157, v195
	v_cvt_pk_bf16_f32 v6, v6, v7
	v_cvt_pk_bf16_f32 v7, v8, v9
	v_mul_f32_e32 v2, v2, v244
	v_mul_f32_e32 v3, v3, v244
	v_mul_f32_e32 v4, v4, v244
	v_mul_f32_e32 v5, v5, v244
	v_fma_f32 v2, v2, v158, v196
	v_fma_f32 v3, v3, v159, v197
	v_fma_f32 v4, v4, v160, v198
	v_fma_f32 v5, v5, v161, v199
	v_cvt_pk_bf16_f32 v2, v2, v3
	v_cvt_pk_bf16_f32 v3, v4, v5
	ds_write_b64 v252, v[14:15] offset:25344
	ds_write_b64 v252, v[10:11] offset:25376
	ds_write_b64 v252, v[6:7] offset:25600
	ds_write_b64 v252, v[2:3] offset:25632
	v_lshl_add_u32 v249, v236, 4, v235
	v_lshrrev_b32_e32 v250, 5, v249
	v_and_b32_e32 v249, 31, v249
	v_lshlrev_b32_e32 v249, 4, v249
	v_lshl_add_u32 v250, s3, 5, v250
	v_mul_u32_u24_e32 v251, 0x210, v250
	v_add_u32_e32 v251, v251, v249
	v_lshl_add_u32 v248, v250, 11, v249
	v_readlane_b32 s12, v255, 9
	v_readlane_b32 s13, v255, 10
	s_lshl_b32 s2, s17, 19
	s_lshl_b32 s8, s48, 9
	s_add_i32 s2, s2, s8
	s_add_u32 s12, s12, s2
	s_addc_u32 s13, s13, 0
	s_waitcnt lgkmcnt(0)
	s_barrier
	ds_read_b128 v[2:5], v251 offset:0
	ds_read_b128 v[6:9], v251 offset:1056
	ds_read_b128 v[10:13], v251 offset:2112
	ds_read_b128 v[14:17], v251 offset:3168
	ds_read_b128 v[18:21], v251 offset:4224
	ds_read_b128 v[22:25], v251 offset:5280
	ds_read_b128 v[26:29], v251 offset:6336
	ds_read_b128 v[30:33], v251 offset:7392
	ds_read_b128 v[34:37], v251 offset:8448
	ds_read_b128 v[38:41], v251 offset:9504
	ds_read_b128 v[42:45], v251 offset:10560
	ds_read_b128 v[46:49], v251 offset:11616
	ds_read_b128 v[50:53], v251 offset:12672
	ds_read_b128 v[54:57], v251 offset:13728
	ds_read_b128 v[58:61], v251 offset:14784
	ds_read_b128 v[62:65], v251 offset:15840
	s_waitcnt lgkmcnt(15)
	global_store_dwordx4 v248, v[2:5], s[12:13]
	s_waitcnt lgkmcnt(14)
	s_add_u32 s14, s12, 0x1000
	s_addc_u32 s15, s13, 0
	global_store_dwordx4 v248, v[6:9], s[14:15]
	s_waitcnt lgkmcnt(13)
	s_add_u32 s14, s12, 0x2000
	s_addc_u32 s15, s13, 0
	global_store_dwordx4 v248, v[10:13], s[14:15]
	s_waitcnt lgkmcnt(12)
	s_add_u32 s14, s12, 0x3000
	s_addc_u32 s15, s13, 0
	global_store_dwordx4 v248, v[14:17], s[14:15]
	s_waitcnt lgkmcnt(11)
	s_add_u32 s14, s12, 0x4000
	s_addc_u32 s15, s13, 0
	global_store_dwordx4 v248, v[18:21], s[14:15]
	s_waitcnt lgkmcnt(10)
	s_add_u32 s14, s12, 0x5000
	s_addc_u32 s15, s13, 0
	global_store_dwordx4 v248, v[22:25], s[14:15]
	s_waitcnt lgkmcnt(9)
	s_add_u32 s14, s12, 0x6000
	s_addc_u32 s15, s13, 0
	global_store_dwordx4 v248, v[26:29], s[14:15]
	s_waitcnt lgkmcnt(8)
	s_add_u32 s14, s12, 0x7000
	s_addc_u32 s15, s13, 0
	global_store_dwordx4 v248, v[30:33], s[14:15]
	s_waitcnt lgkmcnt(7)
	s_add_u32 s14, s12, 0x8000
	s_addc_u32 s15, s13, 0
	global_store_dwordx4 v248, v[34:37], s[14:15]
	s_waitcnt lgkmcnt(6)
	s_add_u32 s14, s12, 0x9000
	s_addc_u32 s15, s13, 0
	global_store_dwordx4 v248, v[38:41], s[14:15]
	s_waitcnt lgkmcnt(5)
	s_add_u32 s14, s12, 0xa000
	s_addc_u32 s15, s13, 0
	global_store_dwordx4 v248, v[42:45], s[14:15]
	s_waitcnt lgkmcnt(4)
	s_add_u32 s14, s12, 0xb000
	s_addc_u32 s15, s13, 0
	global_store_dwordx4 v248, v[46:49], s[14:15]
	s_waitcnt lgkmcnt(3)
	s_add_u32 s14, s12, 0xc000
	s_addc_u32 s15, s13, 0
	global_store_dwordx4 v248, v[50:53], s[14:15]
	s_waitcnt lgkmcnt(2)
	s_add_u32 s14, s12, 0xd000
	s_addc_u32 s15, s13, 0
	global_store_dwordx4 v248, v[54:57], s[14:15]
	s_waitcnt lgkmcnt(1)
	s_add_u32 s14, s12, 0xe000
	s_addc_u32 s15, s13, 0
	global_store_dwordx4 v248, v[58:61], s[14:15]
	s_waitcnt lgkmcnt(0)
	s_add_u32 s14, s12, 0xf000
	s_addc_u32 s15, s13, 0
	global_store_dwordx4 v248, v[62:65], s[14:15]
	s_branch .LBB0_561

.LBB0_893:
	s_cmpk_lt_i32 s67, 192
	s_cbranch_scc1 .Ladh_skip
	v_readlane_b32 s1, v254, 61
	s_mov_b32 s20, -1
	s_mov_b32 s2, 0
	s_cmp_eq_u32 s1, 3
	s_cselect_b32 s20, 1, s20
	s_cselect_b32 s2, 0, s2
	s_cmp_eq_u32 s1, 12
	s_cselect_b32 s20, 2, s20
	s_cselect_b32 s2, 0, s2
	s_cmp_eq_u32 s1, 19
	s_cselect_b32 s20, 3, s20
	s_cselect_b32 s2, 0, s2
	s_cmp_eq_u32 s1, 8
	s_cselect_b32 s20, 0, s20
	s_cselect_b32 s2, 256, s2
	s_cmp_lt_i32 s20, 0
	s_cbranch_scc1 .Ladh_skip
	v_readlane_b32 s0, v254, 63
	s_sub_i32 s3, s67, 192
	s_add_i32 s3, s3, s2
	s_cmpk_ge_i32 s3, 0x120
	s_cbranch_scc1 .Ladh_skip
	s_load_dwordx4 s[8:11], s[60:61], 0x38
	s_load_dwordx4 s[12:15], s[60:61], 0x48
	v_mbcnt_lo_u32_b32 v0, -1, 0
	v_mbcnt_hi_u32_b32 v0, -1, v0
	s_lshl_b32 s16, s0, 14
	s_lshl_b32 s1, s0, 9
	v_lshl_add_u32 v18, v0, 2, s1
	v_lshl_add_u32 v19, v0, 4, s16
	s_waitcnt lgkmcnt(0)
	s_add_u32 s6, s8, 0x1000
	s_addc_u32 s7, s9, 0
	global_load_dword v26, v18, s[10:11]
	global_load_dword v27, v18, s[10:11] offset:256
	global_load_dword v28, v18, s[8:9]
	global_load_dword v29, v18, s[8:9] offset:256
	global_load_dword v30, v18, s[6:7]
	global_load_dword v31, v18, s[6:7] offset:256
	s_waitcnt vmcnt(0)
	v_mul_f32_e32 v74, 0xbfb8aa3b, v26
	v_mul_f32_e32 v75, 0xbfb8aa3b, v27
	v_mul_f32_e32 v76, 0xbfb8aa3b, v28
	v_mul_f32_e32 v77, 0xbfb8aa3b, v29
	v_mul_f32_e32 v78, 0xbfb8aa3b, v30
	v_mul_f32_e32 v79, 0xbfb8aa3b, v31
	v_exp_f32_e32 v74, v74
	v_exp_f32_e32 v75, v75
	v_exp_f32_e32 v76, v76
	v_exp_f32_e32 v77, v77
	v_exp_f32_e32 v78, v78
	v_exp_f32_e32 v79, v79
	v_add_f32_e32 v74, 1.0, v74
	v_add_f32_e32 v75, 1.0, v75
	v_add_f32_e32 v76, 1.0, v76
	v_add_f32_e32 v77, 1.0, v77
	v_add_f32_e32 v78, 1.0, v78
	v_add_f32_e32 v79, 1.0, v79
	v_rcp_f32_e32 v74, v74
	v_rcp_f32_e32 v75, v75
	v_rcp_f32_e32 v76, v76
	v_rcp_f32_e32 v77, v77
	v_rcp_f32_e32 v78, v78
	v_rcp_f32_e32 v79, v79
	v_mul_f32_e32 v26, v26, v74
	v_mul_f32_e32 v27, v27, v75
	v_mul_f32_e32 v28, v28, v76
	v_mul_f32_e32 v29, v29, v77
	v_mul_f32_e32 v30, v30, v78
	v_mul_f32_e32 v31, v31, v79
	v_mov_b32_e32 v90, v26
	v_mov_b32_e32 v91, v28
	v_mov_b32_e32 v92, v30
	v_mov_b32_e32 v93, 0
	v_mov_b32_e32 v94, v27
	v_mov_b32_e32 v95, v29
	v_mov_b32_e32 v96, v31
	v_mov_b32_e32 v97, 0
	ds_write_b128 v19, v[90:93]
	ds_write_b128 v19, v[94:97] offset:1024
	v_lshrrev_b32_e32 v20, 3, v0
	v_and_b32_e32 v21, 7, v0
	v_mul_u32_u24_e32 v22, 0x9000, v20
	v_lshl_add_u32 v22, v21, 4, v22
	s_mul_i32 s17, s0, 0x480000
	s_mul_i32 s1, s20, 0x2400000
	s_add_u32 s17, s17, s1
	s_add_u32 s12, s12, s17
	s_addc_u32 s13, s13, 0
	s_mul_i32 s1, s20, 0x9000
	s_add_u32 s14, s14, s1
	s_addc_u32 s15, s15, 0
	v_lshl_add_u32 v23, v20, 4, s16
	s_mul_i32 s17, s0, 0x180
	s_add_i32 s17, s17, 131072
	v_readlane_b32 s8, v255, 7
	v_readlane_b32 s9, v255, 8
	s_mul_i32 s1, s20, 0x1b000
	s_add_i32 s1, s1, 0x100000
	s_add_u32 s8, s8, s1
	s_addc_u32 s9, s9, 0
	s_mov_b32 s18, s3
	s_waitcnt lgkmcnt(0)
	v_lshl_add_u32 v94, v21, 4, s17
	s_mov_b32 s17, 131072
	v_lshl_add_u32 v95, v0, 2, s17
	v_lshlrev_b32_e32 v96, 2, v0

.Lads_join:
	s_barrier
	s_add_i32 s18, s18, 256
	s_cmpk_lt_i32 s18, 0x100
	s_cbranch_scc1 .Lads_pass

PROG:
	.byte	0, 0, 1
	.byte	1, 0, 1
	.byte	3, 0, 1
	.byte	4, 0, 1
	.byte	1, 1, 1
	.byte	5, 0, 1
	.byte	6, 0, 1
	.byte	7, 0, 1
	.byte	8, 0, 1
	.byte	3, 1, 1
	.byte	4, 1, 1
	.byte	3, 2, 1
	.byte	4, 2, 1
	.byte	2, 5, 1
	.byte	9, 0, 0
	.byte	10, 0, 1
	.byte	11, 0, 1
	.byte	8, 1, 1
	.byte	3, 3, 1
	.byte	4, 3, 1
	.byte	3, 4, 1
	.byte	4, 4, 1
	.byte	12, 0, 1
	.byte	13, 0, 1
	.byte	14, 0, 1
	.byte	8, 2, 1
	.byte	3, 5, 1
	.byte	4, 5, 1
	.byte	3, 6, 1
	.byte	4, 6, 1
	.byte	15, 0, 1
	.byte	16, 0, 1
	.byte	8, 3, 1
	.byte	3, 7, 1
	.byte	4, 7, 0
	.size	PROG, 105

	.protected	BGTAB
	.type	BGTAB,@object
	.globl	BGTAB
	.p2align	4, 0x0
BGTAB:
	.long	0, 0, 0, 0
	.long	0, 0, 0, 0
	.long	2816, 8448, 0, 0
	.long	8448, 12672, 33792, 36352
	.long	0, 0, 0, 0
	.long	0, 0, 0, 0
	.long	0, 0, 0, 0
	.long	0, 0, 0, 0
	.long	0, 0, 0, 0
	.long	12672, 16896, 36352, 36864
	.long	16896, 21120, 40448, 40960
	.long	21120, 25344, 36864, 38400
	.long	25344, 29568, 0, 0
	.long	0, 0, 0, 0
	.long	0, 0, 0, 0
	.long	0, 0, 0, 0
	.long	0, 0, 0, 0
	.long	0, 0, 0, 0
	.long	29568, 33792, 38400, 40448
	.long	0, 0, 0, 0
	.long	0, 0, 0, 0
	.long	0, 0, 0, 0
	.long	0, 0, 0, 0
	.long	0, 0, 0, 0
	.long	0, 0, 0, 0
	.long	0, 0, 0, 0
	.long	0, 0, 0, 0
	.long	0, 0, 0, 0
	.long	0, 0, 0, 0
	.long	0, 0, 0, 0
	.long	0, 0, 0, 0
	.long	0, 0, 0, 0
	.long	0, 0, 0, 0
	.long	0, 0, 0, 0
	.long	0, 0, 0, 0
	.size	BGTAB, 560

	.type	__hip_cuid_dfa6192372e94434,@object
